# LDS-DMA attention loop with count-based VALU weaving instead of cost-weighted spacing
# baseline (speedup 1.0000x reference)
.Lattn_nf_loop:
	ds_read_b128 v[98:101], v82 offset:0
	ds_read_b128 v[102:105], v83 offset:0
	ds_read_b128 v[106:109], v84 offset:0
	ds_read_b128 v[110:113], v85 offset:0
	s_and_b32 s10, s15, 1
	s_xor_b32 s10, s10, 1
	s_lshl_b32 s10, s10, 15
	s_add_i32 s10, s10, s11
	s_add_i32 s6, s10, 0x10000
	s_waitcnt lgkmcnt(3)
	v_mfma_f32_32x32x16_bf16 v[138:153], v[98:101], v[10:13], 0
	ds_read_b128 v[98:101], v82 offset:8192
	s_add_i32 m0, s10, 0x0
	s_nop 0
	global_load_lds_dwordx4 v124, s[64:65]
	s_add_i32 m0, s10, 0x2000
	s_nop 0
	global_load_lds_dwordx4 v124, s[66:67]
	s_waitcnt lgkmcnt(3)
	v_mfma_f32_32x32x16_bf16 v[138:153], v[102:105], v[14:17], v[138:153]
	ds_read_b128 v[102:105], v83 offset:8192
	s_add_i32 m0, s10, 0x4000
	s_nop 0
	global_load_lds_dwordx4 v124, s[68:69]
	s_add_i32 m0, s10, 0x6000
	s_nop 0
	global_load_lds_dwordx4 v124, s[70:71]
	v_add_u32_e32 v124, s36, v124
	s_waitcnt lgkmcnt(3)
	v_mfma_f32_32x32x16_bf16 v[138:153], v[106:109], v[2:5], v[138:153]
	ds_read_b128 v[106:109], v84 offset:8192
	s_add_i32 m0, s6, 0x0
	s_nop 0
	global_load_lds_dwordx4 v125, s[72:73]
	s_add_i32 m0, s6, 0x2000
	s_nop 0
	global_load_lds_dwordx4 v125, s[74:75]
	s_waitcnt lgkmcnt(3)
	v_mfma_f32_32x32x16_bf16 v[138:153], v[110:113], v[6:9], v[138:153]
	ds_read_b128 v[110:113], v85 offset:8192
	s_add_i32 m0, s6, 0x4000
	s_nop 0
	global_load_lds_dwordx4 v125, s[76:77]
	s_add_i32 m0, s6, 0x6000
	s_nop 0
	global_load_lds_dwordx4 v125, s[78:79]
	v_add_u32_e32 v125, s38, v125
	ds_read_b128 v[128:131], v86 offset:0
	ds_read_b128 v[184:187], v86 offset:8192
	ds_read_b128 v[188:191], v86 offset:16384
	ds_read_b128 v[192:195], v86 offset:24576
	s_waitcnt lgkmcnt(7)
	v_mfma_f32_32x32x16_bf16 v[154:169], v[98:101], v[10:13], 0
	ds_read_b128 v[98:101], v82 offset:16384
	v_exp_f32_e32 v138, v138
	v_exp_f32_e32 v139, v139
	v_exp_f32_e32 v140, v140
	v_exp_f32_e32 v141, v141
	v_exp_f32_e32 v142, v142
	v_exp_f32_e32 v143, v143
	v_exp_f32_e32 v144, v144
	v_exp_f32_e32 v145, v145
	s_waitcnt lgkmcnt(7)
	v_mfma_f32_32x32x16_bf16 v[154:169], v[102:105], v[14:17], v[154:169]
	ds_read_b128 v[102:105], v83 offset:16384
	v_add_f32_e32 v122, v138, v122
	v_add_f32_e32 v122, v139, v122
	v_add_f32_e32 v122, v140, v122
	v_add_f32_e32 v122, v141, v122
	v_add_f32_e32 v122, v142, v122
	v_add_f32_e32 v122, v143, v122
	v_add_f32_e32 v122, v144, v122
	v_add_f32_e32 v122, v145, v122
	v_cvt_pk_bf16_f32 v114, v138, v139
	v_cvt_pk_bf16_f32 v115, v140, v141
	v_cvt_pk_bf16_f32 v116, v142, v143
	v_cvt_pk_bf16_f32 v117, v144, v145
	ds_read_b128 v[196:199], v87 offset:0
	ds_read_b128 v[216:219], v87 offset:8192
	ds_read_b128 v[200:203], v87 offset:16384
	ds_read_b128 v[204:207], v87 offset:24576
	s_waitcnt lgkmcnt(11)
	v_mfma_f32_32x32x16_bf16 v[154:169], v[106:109], v[2:5], v[154:169]
	ds_read_b128 v[106:109], v84 offset:16384
	v_exp_f32_e32 v146, v146
	v_exp_f32_e32 v147, v147
	v_exp_f32_e32 v148, v148
	s_waitcnt lgkmcnt(11)
	v_mfma_f32_32x32x16_bf16 v[154:169], v[110:113], v[6:9], v[154:169]
	ds_read_b128 v[110:113], v85 offset:16384
	v_exp_f32_e32 v149, v149
	v_exp_f32_e32 v150, v150
	v_exp_f32_e32 v151, v151
	s_waitcnt lgkmcnt(11)
	v_mfma_f32_32x32x16_bf16 v[18:33], v[128:131], v[114:117], v[18:33]
	v_exp_f32_e32 v152, v152
	v_exp_f32_e32 v153, v153
	v_add_f32_e32 v122, v146, v122
	s_waitcnt lgkmcnt(10)
	v_mfma_f32_32x32x16_bf16 v[34:49], v[184:187], v[114:117], v[34:49]
	v_add_f32_e32 v122, v147, v122
	v_add_f32_e32 v122, v148, v122
	v_add_f32_e32 v122, v149, v122
	s_waitcnt lgkmcnt(9)
	v_mfma_f32_32x32x16_bf16 v[50:65], v[188:191], v[114:117], v[50:65]
	v_add_f32_e32 v122, v150, v122
	v_add_f32_e32 v122, v151, v122
	s_waitcnt lgkmcnt(8)
	v_mfma_f32_32x32x16_bf16 v[66:81], v[192:195], v[114:117], v[66:81]
	v_add_f32_e32 v122, v152, v122
	v_add_f32_e32 v122, v153, v122
	v_cvt_pk_bf16_f32 v118, v146, v147
	v_cvt_pk_bf16_f32 v119, v148, v149
	v_cvt_pk_bf16_f32 v120, v150, v151
	v_cvt_pk_bf16_f32 v121, v152, v153
	ds_read_b128 v[128:131], v88 offset:0
	ds_read_b128 v[184:187], v88 offset:8192
	ds_read_b128 v[188:191], v88 offset:16384
	ds_read_b128 v[192:195], v88 offset:24576
	s_waitcnt lgkmcnt(11)
	v_mfma_f32_32x32x16_bf16 v[138:153], v[98:101], v[10:13], 0
	ds_read_b128 v[98:101], v82 offset:24576
	v_exp_f32_e32 v154, v154
	v_exp_f32_e32 v155, v155
	v_exp_f32_e32 v156, v156
	s_waitcnt lgkmcnt(11)
	v_mfma_f32_32x32x16_bf16 v[138:153], v[102:105], v[14:17], v[138:153]
	ds_read_b128 v[102:105], v83 offset:24576
	v_exp_f32_e32 v157, v157
	v_exp_f32_e32 v158, v158
	v_exp_f32_e32 v159, v159
	s_waitcnt lgkmcnt(11)
	v_mfma_f32_32x32x16_bf16 v[18:33], v[196:199], v[118:121], v[18:33]
	v_exp_f32_e32 v160, v160
	v_exp_f32_e32 v161, v161
	v_add_f32_e32 v122, v154, v122
	s_waitcnt lgkmcnt(10)
	v_mfma_f32_32x32x16_bf16 v[34:49], v[216:219], v[118:121], v[34:49]
	v_add_f32_e32 v122, v155, v122
	v_add_f32_e32 v122, v156, v122
	v_add_f32_e32 v122, v157, v122
	s_waitcnt lgkmcnt(9)
	v_mfma_f32_32x32x16_bf16 v[50:65], v[200:203], v[118:121], v[50:65]
	v_add_f32_e32 v122, v158, v122
	v_add_f32_e32 v122, v159, v122
	s_waitcnt lgkmcnt(8)
	v_mfma_f32_32x32x16_bf16 v[66:81], v[204:207], v[118:121], v[66:81]
	v_add_f32_e32 v122, v160, v122
	v_add_f32_e32 v122, v161, v122
	v_cvt_pk_bf16_f32 v114, v154, v155
	v_cvt_pk_bf16_f32 v115, v156, v157
	v_cvt_pk_bf16_f32 v116, v158, v159
	v_cvt_pk_bf16_f32 v117, v160, v161
	ds_read_b128 v[196:199], v89 offset:0
	ds_read_b128 v[216:219], v89 offset:8192
	ds_read_b128 v[200:203], v89 offset:16384
	ds_read_b128 v[204:207], v89 offset:24576
	s_waitcnt lgkmcnt(11)
	v_mfma_f32_32x32x16_bf16 v[138:153], v[106:109], v[2:5], v[138:153]
	ds_read_b128 v[106:109], v84 offset:24576
	v_exp_f32_e32 v162, v162
	v_exp_f32_e32 v163, v163
	v_exp_f32_e32 v164, v164
	s_waitcnt lgkmcnt(11)
	v_mfma_f32_32x32x16_bf16 v[138:153], v[110:113], v[6:9], v[138:153]
	ds_read_b128 v[110:113], v85 offset:24576
	v_exp_f32_e32 v165, v165
	v_exp_f32_e32 v166, v166
	v_exp_f32_e32 v167, v167
	s_waitcnt lgkmcnt(11)
	v_mfma_f32_32x32x16_bf16 v[18:33], v[128:131], v[114:117], v[18:33]
	v_exp_f32_e32 v168, v168
	v_exp_f32_e32 v169, v169
	v_add_f32_e32 v122, v162, v122
	s_waitcnt lgkmcnt(10)
	v_mfma_f32_32x32x16_bf16 v[34:49], v[184:187], v[114:117], v[34:49]
	v_add_f32_e32 v122, v163, v122
	v_add_f32_e32 v122, v164, v122
	v_add_f32_e32 v122, v165, v122
	s_waitcnt lgkmcnt(9)
	v_mfma_f32_32x32x16_bf16 v[50:65], v[188:191], v[114:117], v[50:65]
	v_add_f32_e32 v122, v166, v122
	v_add_f32_e32 v122, v167, v122
	s_waitcnt lgkmcnt(8)
	v_mfma_f32_32x32x16_bf16 v[66:81], v[192:195], v[114:117], v[66:81]
	v_add_f32_e32 v122, v168, v122
	v_add_f32_e32 v122, v169, v122
	v_cvt_pk_bf16_f32 v118, v162, v163
	v_cvt_pk_bf16_f32 v119, v164, v165
	v_cvt_pk_bf16_f32 v120, v166, v167
	v_cvt_pk_bf16_f32 v121, v168, v169
	ds_read_b128 v[128:131], v90 offset:0
	ds_read_b128 v[184:187], v90 offset:8192
	ds_read_b128 v[188:191], v90 offset:16384
	ds_read_b128 v[192:195], v90 offset:24576
	s_waitcnt lgkmcnt(11)
	v_mfma_f32_32x32x16_bf16 v[154:169], v[98:101], v[10:13], 0
	v_exp_f32_e32 v138, v138
	v_exp_f32_e32 v139, v139
	v_exp_f32_e32 v140, v140
	s_waitcnt lgkmcnt(10)
	v_mfma_f32_32x32x16_bf16 v[154:169], v[102:105], v[14:17], v[154:169]
	v_exp_f32_e32 v141, v141
	v_exp_f32_e32 v142, v142
	v_exp_f32_e32 v143, v143
	s_waitcnt lgkmcnt(9)
	v_mfma_f32_32x32x16_bf16 v[18:33], v[196:199], v[118:121], v[18:33]
	v_exp_f32_e32 v144, v144
	v_exp_f32_e32 v145, v145
	v_add_f32_e32 v122, v138, v122
	s_waitcnt lgkmcnt(8)
	v_mfma_f32_32x32x16_bf16 v[34:49], v[216:219], v[118:121], v[34:49]
	v_add_f32_e32 v122, v139, v122
	v_add_f32_e32 v122, v140, v122
	v_add_f32_e32 v122, v141, v122
	s_waitcnt lgkmcnt(7)
	v_mfma_f32_32x32x16_bf16 v[50:65], v[200:203], v[118:121], v[50:65]
	v_add_f32_e32 v122, v142, v122
	v_add_f32_e32 v122, v143, v122
	s_waitcnt lgkmcnt(6)
	v_mfma_f32_32x32x16_bf16 v[66:81], v[204:207], v[118:121], v[66:81]
	v_add_f32_e32 v122, v144, v122
	v_add_f32_e32 v122, v145, v122
	v_cvt_pk_bf16_f32 v114, v138, v139
	v_cvt_pk_bf16_f32 v115, v140, v141
	v_cvt_pk_bf16_f32 v116, v142, v143
	v_cvt_pk_bf16_f32 v117, v144, v145
	ds_read_b128 v[196:199], v91 offset:0
	ds_read_b128 v[216:219], v91 offset:8192
	ds_read_b128 v[200:203], v91 offset:16384
	ds_read_b128 v[204:207], v91 offset:24576
	s_waitcnt lgkmcnt(9)
	v_mfma_f32_32x32x16_bf16 v[154:169], v[106:109], v[2:5], v[154:169]
	v_exp_f32_e32 v146, v146
	v_exp_f32_e32 v147, v147
	v_exp_f32_e32 v148, v148
	s_waitcnt lgkmcnt(8)
	v_mfma_f32_32x32x16_bf16 v[154:169], v[110:113], v[6:9], v[154:169]
	v_exp_f32_e32 v149, v149
	v_exp_f32_e32 v150, v150
	v_exp_f32_e32 v151, v151
	s_waitcnt lgkmcnt(7)
	v_mfma_f32_32x32x16_bf16 v[18:33], v[128:131], v[114:117], v[18:33]
	v_exp_f32_e32 v152, v152
	v_exp_f32_e32 v153, v153
	v_add_f32_e32 v122, v146, v122
	s_waitcnt lgkmcnt(6)
	v_mfma_f32_32x32x16_bf16 v[34:49], v[184:187], v[114:117], v[34:49]
	v_add_f32_e32 v122, v147, v122
	v_add_f32_e32 v122, v148, v122
	v_add_f32_e32 v122, v149, v122
	s_waitcnt lgkmcnt(5)
	v_mfma_f32_32x32x16_bf16 v[50:65], v[188:191], v[114:117], v[50:65]
	v_add_f32_e32 v122, v150, v122
	v_add_f32_e32 v122, v151, v122
	s_waitcnt lgkmcnt(4)
	v_mfma_f32_32x32x16_bf16 v[66:81], v[192:195], v[114:117], v[66:81]
	v_add_f32_e32 v122, v152, v122
	v_add_f32_e32 v122, v153, v122
	v_cvt_pk_bf16_f32 v118, v146, v147
	v_cvt_pk_bf16_f32 v119, v148, v149
	v_cvt_pk_bf16_f32 v120, v150, v151
	v_cvt_pk_bf16_f32 v121, v152, v153
	ds_read_b128 v[128:131], v92 offset:0
	ds_read_b128 v[184:187], v92 offset:8192
	ds_read_b128 v[188:191], v92 offset:16384
	ds_read_b128 v[192:195], v92 offset:24576
	s_waitcnt lgkmcnt(7)
	v_mfma_f32_32x32x16_bf16 v[18:33], v[196:199], v[118:121], v[18:33]
	v_exp_f32_e32 v154, v154
	v_exp_f32_e32 v155, v155
	v_exp_f32_e32 v156, v156
	v_exp_f32_e32 v157, v157
	v_exp_f32_e32 v158, v158
	s_waitcnt lgkmcnt(6)
	v_mfma_f32_32x32x16_bf16 v[34:49], v[216:219], v[118:121], v[34:49]
	v_exp_f32_e32 v159, v159
	v_exp_f32_e32 v160, v160
	v_exp_f32_e32 v161, v161
	v_add_f32_e32 v122, v154, v122
	v_add_f32_e32 v122, v155, v122
	s_waitcnt lgkmcnt(5)
	v_mfma_f32_32x32x16_bf16 v[50:65], v[200:203], v[118:121], v[50:65]
	v_add_f32_e32 v122, v156, v122
	v_add_f32_e32 v122, v157, v122
	v_add_f32_e32 v122, v158, v122
	v_add_f32_e32 v122, v159, v122
	v_add_f32_e32 v122, v160, v122
	s_waitcnt lgkmcnt(4)
	v_mfma_f32_32x32x16_bf16 v[66:81], v[204:207], v[118:121], v[66:81]
	v_add_f32_e32 v122, v161, v122
	v_xor_b32_e32 v82, 0x8000, v82
	v_xor_b32_e32 v83, 0x8000, v83
	v_xor_b32_e32 v84, 0x8000, v84
	v_xor_b32_e32 v85, 0x8000, v85
	v_cvt_pk_bf16_f32 v114, v154, v155
	v_cvt_pk_bf16_f32 v115, v156, v157
	v_cvt_pk_bf16_f32 v116, v158, v159
	v_cvt_pk_bf16_f32 v117, v160, v161
	ds_read_b128 v[196:199], v93 offset:0
	ds_read_b128 v[216:219], v93 offset:8192
	ds_read_b128 v[200:203], v93 offset:16384
	ds_read_b128 v[204:207], v93 offset:24576
	s_waitcnt lgkmcnt(7)
	v_mfma_f32_32x32x16_bf16 v[18:33], v[128:131], v[114:117], v[18:33]
	v_exp_f32_e32 v162, v162
	v_exp_f32_e32 v163, v163
	v_exp_f32_e32 v164, v164
	v_exp_f32_e32 v165, v165
	s_waitcnt lgkmcnt(6)
	v_mfma_f32_32x32x16_bf16 v[34:49], v[184:187], v[114:117], v[34:49]
	v_exp_f32_e32 v166, v166
	v_exp_f32_e32 v167, v167
	v_exp_f32_e32 v168, v168
	v_exp_f32_e32 v169, v169
	s_waitcnt lgkmcnt(5)
	v_mfma_f32_32x32x16_bf16 v[50:65], v[188:191], v[114:117], v[50:65]
	v_add_f32_e32 v122, v162, v122
	v_add_f32_e32 v122, v163, v122
	v_add_f32_e32 v122, v164, v122
	v_add_f32_e32 v122, v165, v122
	s_waitcnt lgkmcnt(4)
	v_mfma_f32_32x32x16_bf16 v[66:81], v[192:195], v[114:117], v[66:81]
	v_add_f32_e32 v122, v166, v122
	v_add_f32_e32 v122, v167, v122
	v_add_f32_e32 v122, v168, v122
	v_add_f32_e32 v122, v169, v122
	v_cvt_pk_bf16_f32 v118, v162, v163
	v_cvt_pk_bf16_f32 v119, v164, v165
	v_cvt_pk_bf16_f32 v120, v166, v167
	v_cvt_pk_bf16_f32 v121, v168, v169
	s_waitcnt lgkmcnt(3)
	s_nop 0
	v_mfma_f32_32x32x16_bf16 v[18:33], v[196:199], v[118:121], v[18:33]
	v_xor_b32_e32 v86, 0x8000, v86
	v_xor_b32_e32 v87, 0x8000, v87
	s_waitcnt lgkmcnt(2)
	v_mfma_f32_32x32x16_bf16 v[34:49], v[216:219], v[118:121], v[34:49]
	v_xor_b32_e32 v88, 0x8000, v88
	v_xor_b32_e32 v89, 0x8000, v89
	s_waitcnt lgkmcnt(1)
	v_mfma_f32_32x32x16_bf16 v[50:65], v[200:203], v[118:121], v[50:65]
	v_xor_b32_e32 v90, 0x8000, v90
	v_xor_b32_e32 v91, 0x8000, v91
	s_waitcnt lgkmcnt(0)
	v_mfma_f32_32x32x16_bf16 v[66:81], v[204:207], v[118:121], v[66:81]
	v_xor_b32_e32 v92, 0x8000, v92
	v_xor_b32_e32 v93, 0x8000, v93
	s_waitcnt vmcnt(0)
	s_waitcnt lgkmcnt(0)
	s_barrier
	s_add_i32 s15, s15, 1
	s_cmp_eq_u32 s15, 34
	s_cbranch_scc0 .Lattn_nf_loop
	v_readlane_b32 s64, v175, 0
	v_readlane_b32 s65, v175, 1
	v_readlane_b32 s66, v175, 2
	v_readlane_b32 s67, v175, 3
	v_readlane_b32 s68, v175, 4
	v_readlane_b32 s69, v175, 5
	v_readlane_b32 s70, v175, 6
	v_readlane_b32 s71, v175, 7
	v_readlane_b32 s72, v175, 8
	v_readlane_b32 s73, v175, 9
	v_readlane_b32 s74, v175, 10
	v_readlane_b32 s75, v175, 11
	v_readlane_b32 s76, v175, 12
	v_readlane_b32 s77, v175, 13
	v_readlane_b32 s78, v175, 14
	v_readlane_b32 s79, v175, 15
	s_nop 4
	s_mov_b32 s10, 0x3fb8aa3b
	s_mov_b32 s11, 0xc2ce8ed0
	s_mov_b32 s6, 0x42b17218
	v_cmp_eq_u32_e64 s[40:41], 0, v179
	s_lshl_b32 s30, s14, 1
	v_lshlrev_b32_e32 v196, 3, v178
	v_mov_b32_e32 v197, 0
	v_lshlrev_b32_e32 v198, 4, v179
	v_or3_b32 v198, v198, v177, v180
	v_ashrrev_i32_e32 v199, 31, v198
	v_lshlrev_b64 v[198:199], 11, v[198:199]
	s_mov_b64 s[100:101], 0x18a10000
	v_lshl_add_u64 v[198:199], s[42:43], 0, v[198:199]
	v_lshl_add_u64 v[198:199], v[198:199], 0, s[30:31]
	v_lshl_add_u64 v[198:199], v[198:199], 0, v[196:197]
	v_lshl_add_u64 v[198:199], v[198:199], 0, s[100:101]
	global_load_dwordx2 v[146:147], v[198:199], off
	global_load_dwordx2 v[148:149], v[198:199], off offset:32
	global_load_dwordx2 v[150:151], v[198:199], off offset:64
	global_load_dwordx2 v[152:153], v[198:199], off offset:96
	global_load_dwordx2 v[188:189], v[198:199], off offset:128
	global_load_dwordx2 v[190:191], v[198:199], off offset:160
	global_load_dwordx2 v[192:193], v[198:199], off offset:192
	global_load_dwordx2 v[194:195], v[198:199], off offset:224
	s_mov_b64 s[100:101], exec
	s_and_b64 exec, exec, s[4:5]
	s_cbranch_execz .Lpop_skip
	v_readlane_b32 s14, v255, 22
	v_readlane_b32 s15, v255, 23
	v_mov_b32_e32 v224, 1
	s_nop 4
	global_atomic_add v224, v0, v224, s[14:15] sc0
